# stick-breaking walk: exit once every row's carry is <= 2^-134 (every later weight rounds to bf16 zero, so the result is bit-identical) instead of waiting for f32 underflow to 0
# speedup vs baseline: 1.0077x; 1.0053x over previous
.LBB0_400:
	v_cmp_ge_f32_e32 vcc, 0x8000, v146
	s_cmp_eq_u64 vcc, exec
	s_mov_b64 s[34:35], -1
	s_cbranch_scc1 .LBB0_399
	s_cmp_eq_u32 s80, 2
	s_waitcnt vmcnt(5)
	ds_write_b128 v161, v[64:67]
	s_waitcnt vmcnt(4)
	ds_write_b128 v161, v[68:71] offset:512
	s_waitcnt vmcnt(1)
	ds_write_b128 v161, v[72:75] offset:1024
	s_waitcnt vmcnt(0)
	ds_write_b128 v161, v[76:79] offset:1536
	s_cbranch_scc1 .LBB0_403
	global_load_dwordx4 v[108:111], v[138:139], off offset:-4096
	global_load_dwordx4 v[112:115], v[138:139], off offset:-4064
	global_load_dwordx4 v[64:67], v[136:137], off offset:-4096
	global_load_dwordx4 v[68:71], v[136:137], off offset:-3072
	global_load_dwordx4 v[116:119], v[138:139], off offset:-4032
	global_load_dwordx4 v[120:123], v[138:139], off offset:-4000
	global_load_dwordx4 v[72:75], v[136:137], off offset:-2048
	global_load_dwordx4 v[76:79], v[136:137], off offset:-1024
	v_lshl_add_u64 v[138:139], v[138:139], 0, s[0:1]
	v_lshl_add_u64 v[136:137], v[136:137], 0, s[0:1]
	s_branch .LBB0_404
